# attention tile loop: ws base folded into the K/V DMA pointers at block setup (4 VALU 64-bit adds per tile removed from the loop head)
# speedup vs baseline: 1.0005x; 1.0005x over previous
.LBB0_34:
	v_mov_b32_e32 v12, v208
	s_xor_b64 s[84:85], s[86:87], -1
	v_readfirstlane_b32 s56, v12
	s_ashr_i32 s58, s56, 6
	s_and_b64 s[60:61], s[86:87], exec
	v_and_b32_e32 v13, 63, v12
	s_cselect_b32 s57, s33, s11
	s_lshl_b32 s27, s57, 8
	v_lshl_or_b32 v0, s58, 9, v13
	s_or_b32 s53, s27, s52
	v_ashrrev_i32_e32 v0, 4, v0
	v_xor_b32_e32 v2, v0, v12
	v_add_u32_e32 v0, s53, v0
	v_ashrrev_i32_e32 v1, 31, v0
	v_lshlrev_b64 v[0:1], 10, v[0:1]
	v_lshlrev_b32_e32 v2, 4, v2
	s_lshl_b32 s27, s58, 3
	v_lshl_add_u64 v[0:1], s[72:73], 0, v[0:1]
	v_and_b32_e32 v144, 0xf0, v2
	s_lshl_b32 s59, s58, 13
	s_add_i32 s60, 0, 0x18000
	v_lshl_add_u64 v[0:1], v[0:1], 0, v[144:145]
	s_add_i32 m0, s60, s59
	s_or_b32 s61, s27, 1
	global_load_lds_dwordx4 v[0:1], off
	v_lshl_or_b32 v0, s61, 6, v13
	v_ashrrev_i32_e32 v0, 4, v0
	v_xor_b32_e32 v2, v0, v12
	v_add_u32_e32 v0, s53, v0
	v_ashrrev_i32_e32 v1, 31, v0
	v_lshlrev_b64 v[0:1], 10, v[0:1]
	v_lshlrev_b32_e32 v2, 4, v2
	v_lshl_add_u64 v[0:1], s[72:73], 0, v[0:1]
	v_and_b32_e32 v144, 0xf0, v2
	s_lshl_b32 s61, s61, 10
	v_lshl_add_u64 v[0:1], v[0:1], 0, v[144:145]
	s_add_i32 m0, s60, s61
	s_or_b32 s61, s27, 2
	global_load_lds_dwordx4 v[0:1], off
	v_lshl_or_b32 v0, s61, 6, v13
	v_ashrrev_i32_e32 v0, 4, v0
	v_xor_b32_e32 v2, v0, v12
	v_add_u32_e32 v0, s53, v0
	v_ashrrev_i32_e32 v1, 31, v0
	v_lshlrev_b64 v[0:1], 10, v[0:1]
	v_lshlrev_b32_e32 v2, 4, v2
	v_lshl_add_u64 v[0:1], s[72:73], 0, v[0:1]
	v_and_b32_e32 v144, 0xf0, v2
	s_lshl_b32 s61, s61, 10
	v_lshl_add_u64 v[0:1], v[0:1], 0, v[144:145]
	s_add_i32 m0, s60, s61
	s_or_b32 s61, s27, 3
	global_load_lds_dwordx4 v[0:1], off
	v_lshl_or_b32 v0, s61, 6, v13
	v_ashrrev_i32_e32 v0, 4, v0
	v_xor_b32_e32 v2, v0, v12
	v_add_u32_e32 v0, s53, v0
	v_ashrrev_i32_e32 v1, 31, v0
	v_lshlrev_b64 v[0:1], 10, v[0:1]
	v_lshlrev_b32_e32 v2, 4, v2
	v_lshl_add_u64 v[0:1], s[72:73], 0, v[0:1]
	v_and_b32_e32 v144, 0xf0, v2
	s_lshl_b32 s61, s61, 10
	v_lshl_add_u64 v[0:1], v[0:1], 0, v[144:145]
	s_add_i32 m0, s60, s61
	s_or_b32 s61, s27, 4
	global_load_lds_dwordx4 v[0:1], off
	v_lshl_or_b32 v0, s61, 6, v13
	v_ashrrev_i32_e32 v0, 4, v0
	v_xor_b32_e32 v2, v0, v12
	v_add_u32_e32 v0, s53, v0
	v_ashrrev_i32_e32 v1, 31, v0
	v_lshlrev_b64 v[0:1], 10, v[0:1]
	v_lshlrev_b32_e32 v2, 4, v2
	v_lshl_add_u64 v[0:1], s[72:73], 0, v[0:1]
	v_and_b32_e32 v144, 0xf0, v2
	s_lshl_b32 s61, s61, 10
	v_lshl_add_u64 v[0:1], v[0:1], 0, v[144:145]
	s_add_i32 m0, s60, s61
	s_or_b32 s61, s27, 5
	global_load_lds_dwordx4 v[0:1], off
	v_lshl_or_b32 v0, s61, 6, v13
	v_ashrrev_i32_e32 v0, 4, v0
	v_xor_b32_e32 v2, v0, v12
	v_add_u32_e32 v0, s53, v0
	v_ashrrev_i32_e32 v1, 31, v0
	v_lshlrev_b64 v[0:1], 10, v[0:1]
	v_lshlrev_b32_e32 v2, 4, v2
	v_lshl_add_u64 v[0:1], s[72:73], 0, v[0:1]
	v_and_b32_e32 v144, 0xf0, v2
	s_lshl_b32 s61, s61, 10
	v_lshl_add_u64 v[0:1], v[0:1], 0, v[144:145]
	s_add_i32 m0, s60, s61
	s_or_b32 s61, s27, 6
	global_load_lds_dwordx4 v[0:1], off
	v_lshl_or_b32 v0, s61, 6, v13
	v_ashrrev_i32_e32 v0, 4, v0
	v_xor_b32_e32 v2, v0, v12
	v_add_u32_e32 v0, s53, v0
	v_ashrrev_i32_e32 v1, 31, v0
	v_lshlrev_b64 v[0:1], 10, v[0:1]
	v_lshlrev_b32_e32 v2, 4, v2
	v_lshl_add_u64 v[0:1], s[72:73], 0, v[0:1]
	v_and_b32_e32 v144, 0xf0, v2
	s_lshl_b32 s61, s61, 10
	v_lshl_add_u64 v[0:1], v[0:1], 0, v[144:145]
	s_add_i32 m0, s60, s61
	s_or_b32 s27, s27, 7
	global_load_lds_dwordx4 v[0:1], off
	v_lshl_or_b32 v0, s27, 6, v13
	v_ashrrev_i32_e32 v0, 4, v0
	v_xor_b32_e32 v2, v0, v12
	v_add_u32_e32 v0, s53, v0
	v_ashrrev_i32_e32 v1, 31, v0
	v_lshlrev_b64 v[0:1], 10, v[0:1]
	v_lshlrev_b32_e32 v2, 4, v2
	v_lshl_add_u64 v[0:1], s[72:73], 0, v[0:1]
	v_and_b32_e32 v144, 0xf0, v2
	s_lshl_b32 s27, s27, 10
	v_lshl_add_u64 v[0:1], v[0:1], 0, v[144:145]
	s_add_i32 m0, s60, s27
	s_lshl_b32 s27, s58, 11
	global_load_lds_dwordx4 v[0:1], off
	v_lshl_or_b32 v1, s58, 7, v13
	v_ashrrev_i32_e32 v0, 4, v1
	v_xor_b32_e32 v2, v0, v12
	v_lshlrev_b32_e32 v0, 9, v0
	v_lshlrev_b32_e32 v2, 3, v2
	v_and_or_b32 v0, v2, s3, v0
	v_bfe_u32 v2, v12, 4, 2
	v_xor_b32_e32 v2, v2, v12
	v_lshlrev_b32_e32 v2, 3, v2
	v_lshlrev_b32_e32 v3, 9, v1
	v_and_b32_e32 v14, 56, v2
	v_or_b32_e32 v1, 64, v1
	v_and_or_b32 v2, v3, s5, v14
	v_ashrrev_i32_e32 v3, 4, v1
	v_xor_b32_e32 v4, v3, v12
	v_lshlrev_b32_e32 v3, 9, v3
	v_lshlrev_b32_e32 v4, 3, v4
	v_and_or_b32 v4, v4, s3, v3
	v_lshrrev_b32_e32 v3, 4, v1
	v_xor_b32_e32 v3, v3, v12
	v_lshlrev_b32_e32 v8, 9, v1
	v_lshlrev_b32_e32 v1, 3, v3
	v_and_b32_e32 v9, 56, v1
	v_ashrrev_i32_e32 v1, 31, v0
	v_lshlrev_b64 v[0:1], 1, v[0:1]
	s_add_i32 s27, s27, 0
	v_lshl_add_u64 v[6:7], s[74:75], 0, v[0:1]
	s_mov_b32 m0, s27
	v_ashrrev_i32_e32 v3, 31, v2
	v_ashrrev_i32_e32 v5, 31, v4
	global_load_lds_dwordx4 v[6:7], off
	v_lshl_add_u64 v[2:3], v[2:3], 1, s[76:77]
	s_add_i32 m0, s27, 0x4000
	v_lshlrev_b64 v[4:5], 1, v[4:5]
	global_load_lds_dwordx4 v[2:3], off
	v_lshl_add_u64 v[6:7], s[74:75], 0, v[4:5]
	s_add_i32 m0, s27, 0x400
	s_movk_i32 s60, 0xf000
	global_load_lds_dwordx4 v[6:7], off
	v_and_or_b32 v6, v8, s60, v9
	v_ashrrev_i32_e32 v7, 31, v6
	v_lshlrev_b64 v[6:7], 1, v[6:7]
	v_lshl_add_u64 v[8:9], s[76:77], 0, v[6:7]
	s_add_i32 m0, s27, 0x4400
	v_lshl_add_u64 v[10:11], s[78:79], 0, v[0:1]
	global_load_lds_dwordx4 v[8:9], off
	s_add_i32 m0, s27, 0x8000
	v_lshl_add_u64 v[2:3], v[2:3], 0, s[18:19]
	global_load_lds_dwordx4 v[10:11], off
	s_add_i32 m0, s27, 0xc000
	v_lshl_add_u64 v[146:147], s[80:81], 0, v[0:1]
	v_lshl_add_u64 v[146:147], s[54:55], 0, v[146:147]
	global_load_lds_dwordx4 v[2:3], off
	v_lshl_add_u64 v[2:3], s[78:79], 0, v[4:5]
	s_add_i32 m0, s27, 0x8400
	v_lshlrev_b32_e32 v0, 9, v13
	global_load_lds_dwordx4 v[2:3], off
	v_lshl_add_u64 v[2:3], v[8:9], 0, s[18:19]
	s_add_i32 m0, s27, 0xc400
	v_lshl_or_b32 v0, s58, 16, v0
	global_load_lds_dwordx4 v[2:3], off
	v_bfe_u32 v3, v12, 5, 1
	v_and_b32_e32 v2, 31, v12
	v_bitop3_b32 v9, v3, v12, 15 bitop3:0x78
	v_lshlrev_b32_e32 v8, 8, v2
	v_lshlrev_b32_e32 v9, 4, v9
	v_or_b32_e32 v196, v9, v8
	v_or3_b32 v8, s59, v8, v9
	v_add_u32_e32 v197, 0x18000, v8
	v_lshrrev_b32_e32 v8, 1, v12
	v_bitop3_b32 v3, v3, v8, 7 bitop3:0x78
	v_and_or_b32 v0, v0, s5, v14
	s_waitcnt vmcnt(4)
	v_lshlrev_b32_e32 v2, 7, v2
	v_lshlrev_b32_e32 v3, 4, v3
	v_ashrrev_i32_e32 v1, 31, v0
	v_mov_b32_e32 v14, v145
	v_mov_b32_e32 v15, v145
	s_lshl_b32 s57, s57, 2
	s_ashr_i32 s60, s56, 7
	v_or3_b32 v198, v3, v2, s7
	v_lshl_add_u64 v[148:149], s[80:81], 0, v[4:5]
	v_lshl_add_u64 v[148:149], s[54:55], 0, v[148:149]
	v_lshl_add_u64 v[152:153], v[0:1], 1, s[82:83]
	v_lshl_add_u64 v[152:153], s[54:55], 0, v[152:153]
	v_lshl_add_u64 v[154:155], s[82:83], 0, v[6:7]
	v_lshl_add_u64 v[154:155], s[54:55], 0, v[154:155]
	v_mov_b32_e32 v144, v145
	v_mov_b32_e32 v0, v145
	v_mov_b32_e32 v1, v145
	v_mov_b32_e32 v2, v145
	v_mov_b32_e32 v3, v145
	v_mov_b32_e32 v4, v145
	v_mov_b32_e32 v5, v145
	v_mov_b32_e32 v6, v145
	v_mov_b32_e32 v7, v145
	v_mov_b32_e32 v8, v145
	v_mov_b32_e32 v9, v145
	v_mov_b32_e32 v10, v145
	v_mov_b32_e32 v11, v145
	v_mov_b32_e32 v12, v145
	v_mov_b32_e32 v13, v145
	v_mov_b64_e32 v[46:47], v[14:15]
	v_mov_b64_e32 v[78:79], v[14:15]
	v_mov_b64_e32 v[110:111], v[14:15]
	v_mov_b64_e32 v[30:31], v[14:15]
	v_mov_b64_e32 v[62:63], v[14:15]
	v_mov_b64_e32 v[94:95], v[14:15]
	v_mov_b64_e32 v[126:127], v[14:15]
	s_add_i32 s56, s57, 4
	s_add_i32 s57, s60, s57
	s_mov_b32 s61, 0x10000
	s_mov_b32 s60, 0
	v_mov_b64_e32 v[44:45], v[12:13]
	v_mov_b64_e32 v[42:43], v[10:11]
	v_mov_b64_e32 v[40:41], v[8:9]
	v_mov_b64_e32 v[38:39], v[6:7]
	v_mov_b64_e32 v[36:37], v[4:5]
	v_mov_b64_e32 v[34:35], v[2:3]
	v_mov_b64_e32 v[32:33], v[0:1]
	v_mov_b64_e32 v[76:77], v[12:13]
	v_mov_b64_e32 v[74:75], v[10:11]
	v_mov_b64_e32 v[72:73], v[8:9]
	v_mov_b64_e32 v[70:71], v[6:7]
	v_mov_b64_e32 v[68:69], v[4:5]
	v_mov_b64_e32 v[66:67], v[2:3]
	v_mov_b64_e32 v[64:65], v[0:1]
	v_mov_b64_e32 v[108:109], v[12:13]
	v_mov_b64_e32 v[106:107], v[10:11]
	v_mov_b64_e32 v[104:105], v[8:9]
	v_mov_b64_e32 v[102:103], v[6:7]
	v_mov_b64_e32 v[100:101], v[4:5]
	v_mov_b64_e32 v[98:99], v[2:3]
	v_mov_b64_e32 v[96:97], v[0:1]
	v_mov_b64_e32 v[28:29], v[12:13]
	v_mov_b64_e32 v[26:27], v[10:11]
	v_mov_b64_e32 v[24:25], v[8:9]
	v_mov_b64_e32 v[22:23], v[6:7]
	v_mov_b64_e32 v[20:21], v[4:5]
	v_mov_b64_e32 v[18:19], v[2:3]
	v_mov_b64_e32 v[16:17], v[0:1]
	v_mov_b64_e32 v[60:61], v[12:13]
	v_mov_b64_e32 v[58:59], v[10:11]
	v_mov_b64_e32 v[56:57], v[8:9]
	v_mov_b64_e32 v[54:55], v[6:7]
	v_mov_b64_e32 v[52:53], v[4:5]
	v_mov_b64_e32 v[50:51], v[2:3]
	v_mov_b64_e32 v[48:49], v[0:1]
	v_mov_b64_e32 v[92:93], v[12:13]
	v_mov_b64_e32 v[90:91], v[10:11]
	v_mov_b64_e32 v[88:89], v[8:9]
	v_mov_b64_e32 v[86:87], v[6:7]
	v_mov_b64_e32 v[84:85], v[4:5]
	v_mov_b64_e32 v[82:83], v[2:3]
	v_mov_b64_e32 v[80:81], v[0:1]
	v_mov_b64_e32 v[124:125], v[12:13]
	v_mov_b64_e32 v[122:123], v[10:11]
	v_mov_b64_e32 v[120:121], v[8:9]
	v_mov_b64_e32 v[118:119], v[6:7]
	v_mov_b64_e32 v[116:117], v[4:5]
	v_mov_b64_e32 v[114:115], v[2:3]
	v_mov_b64_e32 v[112:113], v[0:1]
	s_mov_b32 s58, 0
	v_mov_b64_e32 v[150:151], v[144:145]
	s_waitcnt lgkmcnt(0)
	s_barrier
.LBB0_35:
	s_mov_b32 s59, s60
	s_add_i32 s60, s58, 2
	s_cmp_ge_u32 s60, s56
	s_cselect_b64 s[86:87], -1, 0
	s_and_b64 vcc, exec, s[86:87]
	s_cbranch_vccnz .LBB0_39
	s_add_i32 s60, s27, s61
	s_mov_b32 m0, s60
	s_nop 0
	global_load_lds_dwordx4 v[146:147], off
	s_add_i32 m0, s60, 0x4000
	s_nop 0
	global_load_lds_dwordx4 v[152:153], off
	s_add_i32 m0, s60, 0x400
	s_nop 0
	global_load_lds_dwordx4 v[148:149], off
	s_add_i32 m0, s60, 0x4400
	s_nop 0
	global_load_lds_dwordx4 v[154:155], off
	s_cmp_gt_i32 s58, s57
	s_cbranch_scc0 .LBB0_40
